# attention: scalar address set-up of each QK segment moved in front of the preceding barrier
# speedup vs baseline: 1.0104x; 1.0005x over previous
; #define ATT_WAIT(n) asm volatile("s_waitcnt vmcnt(" #n ")" ::: "memory")
; #define ATT_BAR() do { asm volatile("s_waitcnt lgkmcnt(0)" ::: "memory"); __builtin_amdgcn_s_barrier(); asm volatile("" ::: "memory"); } while (0)
; #define ATT_ISSUE_K() attn_issue_k(F, KH + (size_t)ATT_TILE((t + 2 < nt) ? t + 2 : nt - 1) * ATT_KB, lds + b2 * ATT_KB)
; #define ATT_ISSUE_V() attn_issue_v(F, VT + (size_t)ATT_TILE((t + 2 < nt) ? t + 2 : nt - 1) * ATT_VB, lds + ATT_VBASE + b2 * ATT_VB)
; __device__ __forceinline__ void attn_unit(const Frame& F, int h, int qb, const float* qw, bool desc) {
;     ...
;         for (int t = 0; t < nt; ++t) {
;             const int tl = ATT_TILE(t), tlp = ATT_TILE(t - 1);
;             ATT_ISSUE_K(); if (t > 0) { ATT_SMPV(tlp, bp); } ATT_WAIT(8); ATT_BAR();
;             ATT_ISSUE_V(); ATT_QK(tl, b0); ATT_WAIT(7); ATT_BAR();
.LBB0_1013:
	s_lshl_b32 s89, s89, 14
	s_add_u32 s92, s42, s89
	s_addc_u32 s93, s43, 0
	s_lshl_b32 s89, s75, 14
	s_add_i32 s89, s89, 0x12000
	s_add_i32 vcc_lo, s89, s59
	s_add_i32 vcc_hi, s89, s60
	s_add_u32 s98, s92, s14
	s_addc_u32 s99, s93, s15
	s_add_u32 s100, s92, s16
	s_addc_u32 s101, s93, s17
	s_mul_i32 s89, s0, 0x6000
	v_add_u32_e32 v2, s89, v174
	v_add_u32_e32 v16, s89, v175
	s_waitcnt vmcnt(8)
	s_waitcnt lgkmcnt(0)
	s_barrier
	s_setprio 1
	s_cmp_gt_i32 s90, s70
	s_cbranch_scc1 .Lmy_attn_skipqk_b
	ds_read_b128 v[4:7], v2
	ds_read_b128 v[8:11], v2 offset:12288
	ds_read_b128 v[12:15], v16
	ds_read_b128 v[186:189], v16 offset:12288
	v_add_u32_e32 v17, s89, v176
	v_add_u32_e32 v185, s89, v177
	ds_read_b128 v[190:193], v17
	ds_read_b128 v[194:197], v17 offset:12288
	ds_read_b128 v[198:201], v185
	ds_read_b128 v[202:205], v185 offset:12288
	s_waitcnt lgkmcnt(5)
	v_mfma_f32_32x32x16_bf16 v[98:113], v[4:7], v[114:117], 0
	v_mfma_f32_32x32x16_bf16 v[98:113], v[12:15], v[118:121], v[98:113]
	ds_read_b128 v[206:209], v2 offset:128
	ds_read_b128 v[210:213], v2 offset:12416
	ds_read_b128 v[214:217], v16 offset:128
	ds_read_b128 v[218:221], v16 offset:12416
	s_waitcnt lgkmcnt(8)
	v_mfma_f32_32x32x16_bf16 v[82:97], v[8:11], v[114:117], 0
	s_mov_b32 m0, vcc_lo
	s_nop 0
	global_load_lds_dwordx4 v164, s[98:99]
	v_mfma_f32_32x32x16_bf16 v[82:97], v[186:189], v[118:121], v[82:97]
	s_mov_b32 m0, vcc_hi
	s_nop 0
	global_load_lds_dwordx4 v164, s[100:101]
	ds_read_b128 v[4:7], v17 offset:128
	ds_read_b128 v[8:11], v17 offset:12416
	ds_read_b128 v[12:15], v185 offset:128
	ds_read_b128 v[186:189], v185 offset:12416
	s_waitcnt lgkmcnt(8)
	v_mfma_f32_32x32x16_bf16 v[98:113], v[190:193], v[122:125], v[98:113]
	v_mfma_f32_32x32x16_bf16 v[98:113], v[198:201], v[126:129], v[98:113]
	v_mfma_f32_32x32x16_bf16 v[82:97], v[194:197], v[122:125], v[82:97]
	v_mfma_f32_32x32x16_bf16 v[82:97], v[202:205], v[126:129], v[82:97]
	ds_read_b128 v[190:193], v2 offset:256
	ds_read_b128 v[194:197], v2 offset:12544
	ds_read_b128 v[198:201], v16 offset:256
	ds_read_b128 v[202:205], v16 offset:12544
	s_waitcnt lgkmcnt(8)
	v_mfma_f32_32x32x16_bf16 v[98:113], v[206:209], v[130:133], v[98:113]
	v_mfma_f32_32x32x16_bf16 v[98:113], v[214:217], v[134:137], v[98:113]
	v_mfma_f32_32x32x16_bf16 v[82:97], v[210:213], v[130:133], v[82:97]
	v_mfma_f32_32x32x16_bf16 v[82:97], v[218:221], v[134:137], v[82:97]
	ds_read_b128 v[206:209], v17 offset:256
	ds_read_b128 v[210:213], v17 offset:12544
	ds_read_b128 v[214:217], v185 offset:256
	ds_read_b128 v[218:221], v185 offset:12544
	s_waitcnt lgkmcnt(8)
	v_mfma_f32_32x32x16_bf16 v[98:113], v[4:7], v[138:141], v[98:113]
	v_mfma_f32_32x32x16_bf16 v[98:113], v[12:15], v[142:145], v[98:113]
	v_mfma_f32_32x32x16_bf16 v[82:97], v[8:11], v[138:141], v[82:97]
	v_mfma_f32_32x32x16_bf16 v[82:97], v[186:189], v[142:145], v[82:97]
	s_waitcnt lgkmcnt(4)
	v_mfma_f32_32x32x16_bf16 v[98:113], v[190:193], v[146:149], v[98:113]
	v_mfma_f32_32x32x16_bf16 v[98:113], v[198:201], v[154:157], v[98:113]
	v_mfma_f32_32x32x16_bf16 v[82:97], v[194:197], v[146:149], v[82:97]
	v_mfma_f32_32x32x16_bf16 v[82:97], v[202:205], v[154:157], v[82:97]
	s_waitcnt lgkmcnt(0)
	v_mfma_f32_32x32x16_bf16 v[98:113], v[206:209], v[150:153], v[98:113]
	v_mfma_f32_32x32x16_bf16 v[98:113], v[214:217], v[158:161], v[98:113]
	v_mfma_f32_32x32x16_bf16 v[82:97], v[210:213], v[150:153], v[82:97]
	v_mfma_f32_32x32x16_bf16 v[82:97], v[218:221], v[158:161], v[82:97]
	s_branch .LBB0_1016

; #define ATT_WAIT(n) asm volatile("s_waitcnt vmcnt(" #n ")" ::: "memory")
; #define ATT_BAR() do { asm volatile("s_waitcnt lgkmcnt(0)" ::: "memory"); __builtin_amdgcn_s_barrier(); asm volatile("" ::: "memory"); } while (0)
; __device__ __forceinline__ void attn_unit(const Frame& F, int h, int qb, const float* qw, bool desc) {
;     ...
;     int kof[4], vof[4];
; #pragma unroll
;     for (int c2 = 0; c2 < 4; ++c2) { const int slot = (((2 * c2 + hh) ^ sz) & 7) << 4; kof[c2] = l31 * 384 + slot; vof[c2] = l31 * 128 + slot; }
;     f32x16 O0, O1, O2, O3, S0, S1;
; #pragma unroll
;     for (int i = 0; i < 16; ++i) { O0[i] = 0.f; O1[i] = 0.f; O2[i] = 0.f; O3[i] = 0.f; S0[i] = 0.f; S1[i] = 0.f; }
;     float l_run = 0.f;
;     ATT_WAIT(7); ATT_BAR();
;     ...
;     int b0 = 0, b2 = 2, bp = 2;
;     if (grpA) {
; #pragma unroll 1
;         for (int t = 0; t < nt; ++t) {
;             const int tl = ATT_TILE(t);
.LBB0_1023:
	s_and_b64 vcc, exec, s[0:1]
	s_cbranch_vccz .LBB0_1003
	s_add_i32 s0, s62, s88
	v_add_u32_e32 v2, s0, v169
	v_mov_b32_e32 v16, v3
	v_mov_b32_e32 v17, v3
	s_lshl_b32 s44, s45, 6
	v_sub_u32_e32 v170, v2, v179
	v_mov_b32_e32 v2, v3
	v_mov_b32_e32 v4, v3
	v_mov_b32_e32 v5, v3
	v_mov_b32_e32 v6, v3
	v_mov_b32_e32 v7, v3
	v_mov_b32_e32 v8, v3
	v_mov_b32_e32 v9, v3
	v_mov_b32_e32 v10, v3
	v_mov_b32_e32 v11, v3
	v_mov_b32_e32 v12, v3
	v_mov_b32_e32 v13, v3
	v_mov_b32_e32 v14, v3
	v_mov_b32_e32 v15, v3
	v_mov_b64_e32 v[80:81], v[16:17]
	v_mov_b64_e32 v[64:65], v[16:17]
	v_mov_b64_e32 v[48:49], v[16:17]
	v_mov_b64_e32 v[32:33], v[16:17]
	s_mov_b32 s33, 2
	s_add_i32 s44, s44, 64
	s_mov_b32 s72, 0
	v_mov_b32_e32 v178, 0
	v_mov_b64_e32 v[78:79], v[14:15]
	v_mov_b64_e32 v[76:77], v[12:13]
	v_mov_b64_e32 v[74:75], v[10:11]
	v_mov_b64_e32 v[72:73], v[8:9]
	v_mov_b64_e32 v[70:71], v[6:7]
	v_mov_b64_e32 v[68:69], v[4:5]
	v_mov_b64_e32 v[66:67], v[2:3]
	v_mov_b64_e32 v[62:63], v[14:15]
	v_mov_b64_e32 v[60:61], v[12:13]
	v_mov_b64_e32 v[58:59], v[10:11]
	v_mov_b64_e32 v[56:57], v[8:9]
	v_mov_b64_e32 v[54:55], v[6:7]
	v_mov_b64_e32 v[52:53], v[4:5]
	v_mov_b64_e32 v[50:51], v[2:3]
	v_mov_b64_e32 v[46:47], v[14:15]
	v_mov_b64_e32 v[44:45], v[12:13]
	v_mov_b64_e32 v[42:43], v[10:11]
	v_mov_b64_e32 v[40:41], v[8:9]
	v_mov_b64_e32 v[38:39], v[6:7]
	v_mov_b64_e32 v[36:37], v[4:5]
	v_mov_b64_e32 v[34:35], v[2:3]
	v_mov_b64_e32 v[30:31], v[14:15]
	v_mov_b64_e32 v[28:29], v[12:13]
	v_mov_b64_e32 v[26:27], v[10:11]
	v_mov_b64_e32 v[24:25], v[8:9]
	v_mov_b64_e32 v[22:23], v[6:7]
	v_mov_b64_e32 v[20:21], v[4:5]
	v_mov_b64_e32 v[18:19], v[2:3]
	s_mov_b32 s73, 0
	s_mov_b32 s74, 2
	s_min_u32 s75, s33, s45
	s_mul_i32 s0, s75, 0x6000
	s_add_u32 s98, s40, s0
	s_addc_u32 s99, s41, 0
	s_mul_i32 vcc_lo, s74, 0x6000
	s_mul_i32 s88, s73, 0x6000
	v_add_u32_e32 v2, s88, v174
	v_add_u32_e32 v16, s88, v175
	s_branch .LBB0_1027

; #define ATT_WAIT(n) asm volatile("s_waitcnt vmcnt(" #n ")" ::: "memory")
; #define ATT_BAR() do { asm volatile("s_waitcnt lgkmcnt(0)" ::: "memory"); __builtin_amdgcn_s_barrier(); asm volatile("" ::: "memory"); } while (0)
; #define ATT_ISSUE_K() attn_issue_k(F, KH + (size_t)ATT_TILE((t + 2 < nt) ? t + 2 : nt - 1) * ATT_KB, lds + b2 * ATT_KB)
; __device__ __forceinline__ void attn_unit(const Frame& F, int h, int qb, const float* qw, bool desc) {
;     ...
;     int b0 = 0, b2 = 2, bp = 2;
;     if (grpA) {
; #pragma unroll 1
;         for (int t = 0; t < nt; ++t) {
;             const int tl = ATT_TILE(t);
;             ATT_ISSUE_K(); ATT_QK(tl, b0); ATT_WAIT(8); ATT_BAR();
.LBB0_1026:
	s_add_i32 s0, s73, 1
	s_cmp_lg_u32 s73, 2
	s_cselect_b32 s73, s0, 0
	s_add_i32 s0, s74, 1
	s_cmp_lg_u32 s74, 2
	s_cselect_b32 s74, s0, 0
	s_add_i32 s72, s72, 64
	s_add_i32 s33, s33, 1
	v_subrev_u32_e32 v170, 64, v170
	s_min_u32 s75, s33, s45
	s_mul_i32 s0, s75, 0x6000
	s_add_u32 s98, s40, s0
	s_addc_u32 s99, s41, 0
	s_mul_i32 vcc_lo, s74, 0x6000
	s_mul_i32 s88, s73, 0x6000
	v_add_u32_e32 v2, s88, v174
	v_add_u32_e32 v16, s88, v175
	s_waitcnt vmcnt(7)
	s_waitcnt lgkmcnt(0)
	s_barrier
	s_cmp_eq_u32 s44, s72
	s_cbranch_scc1 .LBB0_1003
.LBB0_1027:
	s_setprio 1
	s_cmp_le_u32 s72, s70
	s_cselect_b64 s[0:1], -1, 0
	s_cmp_gt_u32 s72, s70
	s_cbranch_scc1 .Lmy_attn_skipqk_a
	ds_read_b128 v[4:7], v2
	ds_read_b128 v[8:11], v2 offset:12288
	ds_read_b128 v[12:15], v16
	ds_read_b128 v[180:183], v16 offset:12288
	v_add_u32_e32 v17, s88, v176
	v_add_u32_e32 v179, s88, v177
	ds_read_b128 v[184:187], v17
	ds_read_b128 v[188:191], v17 offset:12288
	ds_read_b128 v[192:195], v179
	ds_read_b128 v[196:199], v179 offset:12288
	s_waitcnt lgkmcnt(5)
	v_mfma_f32_32x32x16_bf16 v[98:113], v[4:7], v[114:117], 0
	v_mfma_f32_32x32x16_bf16 v[98:113], v[12:15], v[118:121], v[98:113]
	ds_read_b128 v[200:203], v2 offset:128
	ds_read_b128 v[204:207], v2 offset:12416
	ds_read_b128 v[208:211], v16 offset:128
	ds_read_b128 v[212:215], v16 offset:12416
	s_waitcnt lgkmcnt(8)
	v_mfma_f32_32x32x16_bf16 v[82:97], v[8:11], v[114:117], 0
	s_add_i32 m0, vcc_lo, s56
	s_add_u32 s100, s98, s8
	s_addc_u32 s101, s99, s9
	global_load_lds_dwordx4 v164, s[100:101]
	v_mfma_f32_32x32x16_bf16 v[82:97], v[180:183], v[118:121], v[82:97]
	s_add_i32 m0, vcc_lo, s57
	s_add_u32 s100, s98, s10
	s_addc_u32 s101, s99, s11
	global_load_lds_dwordx4 v164, s[100:101]
	s_add_i32 m0, vcc_lo, s58
	s_add_u32 s100, s98, s12
	s_addc_u32 s101, s99, s13
	global_load_lds_dwordx4 v164, s[100:101]
	ds_read_b128 v[4:7], v17 offset:128
	ds_read_b128 v[8:11], v17 offset:12416
	ds_read_b128 v[12:15], v179 offset:128
	ds_read_b128 v[180:183], v179 offset:12416
	s_waitcnt lgkmcnt(8)
	v_mfma_f32_32x32x16_bf16 v[98:113], v[184:187], v[122:125], v[98:113]
	v_mfma_f32_32x32x16_bf16 v[98:113], v[192:195], v[126:129], v[98:113]
	v_mfma_f32_32x32x16_bf16 v[82:97], v[188:191], v[122:125], v[82:97]
	v_mfma_f32_32x32x16_bf16 v[82:97], v[196:199], v[126:129], v[82:97]
	ds_read_b128 v[184:187], v2 offset:256
	ds_read_b128 v[188:191], v2 offset:12544
	ds_read_b128 v[192:195], v16 offset:256
	ds_read_b128 v[196:199], v16 offset:12544
	s_waitcnt lgkmcnt(8)
	v_mfma_f32_32x32x16_bf16 v[98:113], v[200:203], v[130:133], v[98:113]
	v_mfma_f32_32x32x16_bf16 v[98:113], v[208:211], v[134:137], v[98:113]
	v_mfma_f32_32x32x16_bf16 v[82:97], v[204:207], v[130:133], v[82:97]
	v_mfma_f32_32x32x16_bf16 v[82:97], v[212:215], v[134:137], v[82:97]
	ds_read_b128 v[200:203], v17 offset:256
	ds_read_b128 v[204:207], v17 offset:12544
	ds_read_b128 v[208:211], v179 offset:256
	ds_read_b128 v[212:215], v179 offset:12544
	s_waitcnt lgkmcnt(8)
	v_mfma_f32_32x32x16_bf16 v[98:113], v[4:7], v[138:141], v[98:113]
	v_mfma_f32_32x32x16_bf16 v[98:113], v[12:15], v[142:145], v[98:113]
	v_mfma_f32_32x32x16_bf16 v[82:97], v[8:11], v[138:141], v[82:97]
	v_mfma_f32_32x32x16_bf16 v[82:97], v[180:183], v[142:145], v[82:97]
	s_waitcnt lgkmcnt(4)
	v_mfma_f32_32x32x16_bf16 v[98:113], v[184:187], v[146:149], v[98:113]
	v_mfma_f32_32x32x16_bf16 v[98:113], v[192:195], v[154:157], v[98:113]
	v_mfma_f32_32x32x16_bf16 v[82:97], v[188:191], v[146:149], v[82:97]
	v_mfma_f32_32x32x16_bf16 v[82:97], v[196:199], v[154:157], v[82:97]
	s_waitcnt lgkmcnt(0)
	v_mfma_f32_32x32x16_bf16 v[98:113], v[200:203], v[150:153], v[98:113]
	v_mfma_f32_32x32x16_bf16 v[98:113], v[208:211], v[158:161], v[98:113]
	v_mfma_f32_32x32x16_bf16 v[82:97], v[204:207], v[150:153], v[82:97]
	v_mfma_f32_32x32x16_bf16 v[82:97], v[212:215], v[158:161], v[82:97]
	s_branch .LBB0_1030
